# mixer C step-2 epilogue: gate loads and y_c stores lane-transposed so 4 consecutive lanes cover 32 contiguous bytes (ds_bpermute back/forth)
# speedup vs baseline: 1.0102x; 1.0023x over previous
.LBB0_1088:
	global_load_dwordx4 v[4:7], v[24:25], off
	global_load_dwordx4 v[8:11], v[24:25], off offset:16
	s_lshl_b32 s2, s8, 5
	s_add_i32 s6, s2, 0x8000
	s_lshl_b32 s2, s8, 7
	s_add_i32 s7, s2, 0xfffffc00
	s_cmp_gt_i32 s8, 7
	s_cselect_b64 s[4:5], -1, 0
	s_and_b64 s[2:3], s[4:5], exec
	s_cselect_b32 s3, -1, s8
	s_cselect_b32 s9, 8, 2
	s_cselect_b32 s2, s7, s6
	s_cmp_gt_i32 s3, -1
	s_cselect_b64 s[6:7], -1, 0
	s_add_i32 s24, s3, s53
	s_ashr_i32 s3, s2, 31
	v_lshl_add_u64 v[12:13], v[22:23], 0, s[2:3]
	s_lshl_b64 s[10:11], s[24:25], 15
	v_mad_u64_u32 v[40:41], s[16:17], v12, s69, v[26:27]
	v_mad_i32_i24 v41, v13, s69, v41
	v_lshl_add_u64 v[42:43], v[28:29], 0, s[10:11]
	v_readlane_b32 s100, v254, 9
	v_bfe_u32 v104, v52, 2, 3
	v_and_b32_e32 v105, 2, v52
	v_lshlrev_b32_e32 v105, 3, v105
	v_xor_b32_e32 v105, v105, v59
	s_mov_b32 s101, 0
	s_lshr_b32 s100, s100, 4
	v_lshl_add_u32 v2, v104, 5, v105
	v_lshrrev_b32_e32 v106, 2, v0
	v_and_b32_e32 v107, 3, v0
	v_lshlrev_b32_e32 v107, 3, v107
	v_lshl_add_u32 v107, s100, 5, v107
	v_and_b32_e32 v108, 15, v0
	v_lshlrev_b32_e32 v108, 4, v108
	v_lshrrev_b32_e32 v109, 4, v0
	v_lshl_or_b32 v108, v109, 2, v108
	v_and_b32_e32 v109, 3, v0
	v_lshlrev_b32_e32 v109, 6, v109
	v_and_b32_e32 v118, 0x3c, v0
	v_or_b32_e32 v109, v109, v118
	s_branch .LBB0_1090

.LBB0_1094:
	s_add_i32 s6, s4, s19
	v_lshl_or_b32 v73, s6, 4, v21
	v_add_u32_e32 v74, s20, v73
	v_mov_b32_e32 v75, 0
	v_lshl_add_u64 v[74:75], v[74:75], 2, s[0:1]
	global_load_dword v72, v[74:75], off
	v_lshl_or_b32 v73, s6, 4, v106
	v_add_u32_e32 v73, s2, v73
	v_mov_b64_e32 v[74:75], s[14:15]
	v_mad_i64_i32 v[74:75], s[6:7], v73, s69, v[74:75]
	s_mov_b64 s[6:7], 0x7900e00
	v_mov_b32_e32 v76, v107
	v_mov_b32_e32 v77, 0
	v_lshl_add_u64 v[110:111], v[74:75], 0, s[6:7]
	s_movk_i32 s6, 0xf600
	v_mad_i64_i32 v[112:113], s[6:7], v73, s6, v[74:75]
	v_lshl_add_u64 v[110:111], v[110:111], 0, v[76:77]
	global_load_dwordx2 v[64:65], v[110:111], off
	global_load_dwordx2 v[66:67], v[110:111], off offset:32
	global_load_dwordx2 v[68:69], v[110:111], off offset:64
	global_load_dwordx2 v[70:71], v[110:111], off offset:96
	s_mov_b64 s[6:7], 0x18d00600
	v_lshl_add_u64 v[112:113], v[112:113], 0, s[6:7]
	v_lshl_add_u64 v[112:113], v[112:113], 0, v[76:77]
	s_lshr_b32 s6, s5, 5
	v_mov_b32_e32 v16, 0
	s_add_i32 s6, s6, 1
	v_mov_b64_e32 v[42:43], v[40:41]
	v_lshrrev_b32_e32 v94, 4, v53
	v_sub_u32_e32 v95, v58, v53
	v_mov_b32_e32 v17, v16
	v_mov_b32_e32 v18, v16
	v_mov_b32_e32 v19, v16
	v_mov_b32_e32 v12, v16
	v_mov_b32_e32 v13, v16
	v_mov_b32_e32 v14, v16
	v_mov_b32_e32 v15, v16
	v_mov_b32_e32 v8, v16
	v_mov_b32_e32 v9, v16
	v_mov_b32_e32 v10, v16
	v_mov_b32_e32 v11, v16
	v_mov_b32_e32 v4, v16
	v_mov_b32_e32 v5, v16
	v_mov_b32_e32 v6, v16
	v_mov_b32_e32 v7, v16
	global_load_dwordx4 v[44:47], v[42:43], off
	v_lshl_add_u64 v[42:43], v[42:43], 0, 64

.Lmc_ks_last:
	s_waitcnt lgkmcnt(3)
	v_mfma_f32_16x16x32_bf16 v[16:19], v[48:51], v[90:93], v[16:19]
	s_waitcnt lgkmcnt(2)
	v_mfma_f32_16x16x32_bf16 v[12:15], v[78:81], v[90:93], v[12:15]
	s_waitcnt lgkmcnt(1)
	v_mfma_f32_16x16x32_bf16 v[8:11], v[82:85], v[90:93], v[8:11]
	s_waitcnt lgkmcnt(0)
	v_mfma_f32_16x16x32_bf16 v[4:7], v[86:89], v[90:93], v[4:7]
	s_cbranch_scc0 .LBB0_1095
	ds_bpermute_b32 v64, v108, v64
	ds_bpermute_b32 v65, v108, v65
	ds_bpermute_b32 v66, v108, v66
	ds_bpermute_b32 v67, v108, v67
	ds_bpermute_b32 v68, v108, v68
	ds_bpermute_b32 v69, v108, v69
	ds_bpermute_b32 v70, v108, v70
	ds_bpermute_b32 v71, v108, v71
	s_add_i32 s6, s4, s19
	v_lshl_or_b32 v33, s6, 4, v21
	v_add_u32_e32 v2, s20, v33
	v_lshl_add_u64 v[42:43], v[2:3], 2, s[0:1]
	v_mov_b32_e32 v2, v72
	v_add_u32_e32 v33, s2, v33
	v_mov_b64_e32 v[42:43], s[14:15]
	v_mad_i64_i32 v[42:43], s[6:7], v33, s69, v[42:43]
	s_mov_b64 s[6:7], 0x7900e00
	s_nop 0
	v_lshl_add_u64 v[44:45], v[42:43], 0, s[6:7]
	s_movk_i32 s6, 0xf600
	v_mad_i64_i32 v[42:43], s[6:7], v33, s6, v[42:43]
	v_mov_b32_e32 v33, v3
	v_lshl_add_u64 v[46:47], v[44:45], 0, v[32:33]
	s_waitcnt lgkmcnt(0)
	v_mov_b32_e32 v46, v64
	v_mov_b32_e32 v47, v65
	s_mov_b64 s[6:7], 0x18d00600
	v_lshl_add_u64 v[42:43], v[42:43], 0, s[6:7]
	v_mov_b32_e32 v39, v3
	s_add_i32 s4, s4, 1
	s_add_i32 s5, s5, 16
	s_mov_b64 s[6:7], 0x1000
	v_lshl_add_u64 v[40:41], v[40:41], 0, s[6:7]
	s_cmp_eq_u32 s4, s3
	v_add_f32_e32 v16, v2, v16
	v_add_f32_e32 v17, v2, v17
	v_add_f32_e32 v18, v2, v18
	v_add_f32_e32 v19, v2, v19
	v_add_f32_e32 v12, v2, v12
	v_add_f32_e32 v13, v2, v13
	v_add_f32_e32 v14, v2, v14
	v_add_f32_e32 v15, v2, v15
	v_add_f32_e32 v8, v2, v8
	v_add_f32_e32 v9, v2, v9
	v_add_f32_e32 v10, v2, v10
	v_add_f32_e32 v11, v2, v11
	v_lshlrev_b32_e32 v35, 16, v46
	v_mul_f32_e32 v37, 0x3d372713, v35
	v_mul_f32_e32 v37, v37, v35
	v_fma_f32 v37, v37, v35, v35
	v_mul_f32_e32 v37, 0x3f4c422a, v37
	v_add_f32_e32 v37, v37, v37
	v_mul_f32_e32 v37, 0xbfb8aa3b, v37
	v_exp_f32_e32 v37, v37
	v_add_f32_e32 v4, v2, v4
	v_add_f32_e32 v5, v2, v5
	v_add_f32_e32 v6, v2, v6
	v_add_f32_e32 v37, 1.0, v37
	v_rcp_f32_e32 v37, v37
	v_add_f32_e32 v2, v2, v7
	v_mul_f32_e32 v35, v37, v35
	v_mul_f32_e32 v16, v16, v35
	v_and_b32_e32 v35, 0xffff0000, v46
	v_mul_f32_e32 v37, 0x3d372713, v35
	v_mul_f32_e32 v37, v37, v35
	v_fma_f32 v37, v37, v35, v35
	v_mul_f32_e32 v37, 0x3f4c422a, v37
	v_add_f32_e32 v37, v37, v37
	v_mul_f32_e32 v37, 0xbfb8aa3b, v37
	v_exp_f32_e32 v37, v37
	s_nop 0
	v_add_f32_e32 v37, 1.0, v37
	v_rcp_f32_e32 v37, v37
	s_nop 0
	v_mul_f32_e32 v35, v37, v35
	v_mul_f32_e32 v17, v17, v35
	v_cvt_pk_bf16_f32 v16, v16, v17
	v_lshlrev_b32_e32 v17, 16, v47
	v_mul_f32_e32 v35, 0x3d372713, v17
	v_mul_f32_e32 v35, v35, v17
	v_fma_f32 v35, v35, v17, v17
	v_mul_f32_e32 v35, 0x3f4c422a, v35
	v_add_f32_e32 v35, v35, v35
	v_mul_f32_e32 v35, 0xbfb8aa3b, v35
	v_exp_f32_e32 v35, v35
	v_mov_b32_e32 v37, v3
	v_add_f32_e32 v35, 1.0, v35
	v_rcp_f32_e32 v35, v35
	s_nop 0
	v_mul_f32_e32 v17, v35, v17
	v_mul_f32_e32 v17, v18, v17
	v_and_b32_e32 v18, 0xffff0000, v47
	v_mul_f32_e32 v35, 0x3d372713, v18
	v_mul_f32_e32 v35, v35, v18
	v_fma_f32 v35, v35, v18, v18
	v_mul_f32_e32 v35, 0x3f4c422a, v35
	v_add_f32_e32 v35, v35, v35
	v_mul_f32_e32 v35, 0xbfb8aa3b, v35
	v_exp_f32_e32 v35, v35
	s_nop 0
	v_add_f32_e32 v35, 1.0, v35
	v_rcp_f32_e32 v35, v35
	s_nop 0
	v_mul_f32_e32 v18, v35, v18
	v_mul_f32_e32 v18, v19, v18
	v_cvt_pk_bf16_f32 v17, v17, v18
	v_lshl_add_u64 v[18:19], v[42:43], 0, v[32:33]
	v_mov_b32_e32 v35, v3
	ds_bpermute_b32 v116, v109, v16
	ds_bpermute_b32 v117, v109, v17
	v_mov_b32_e32 v16, v66
	v_mov_b32_e32 v17, v67
	v_lshlrev_b32_e32 v18, 16, v16
	v_mul_f32_e32 v19, 0x3d372713, v18
	v_mul_f32_e32 v19, v19, v18
	v_fma_f32 v19, v19, v18, v18
	v_mul_f32_e32 v19, 0x3f4c422a, v19
	v_add_f32_e32 v19, v19, v19
	v_mul_f32_e32 v19, 0xbfb8aa3b, v19
	v_exp_f32_e32 v19, v19
	v_and_b32_e32 v16, 0xffff0000, v16
	v_add_f32_e32 v19, 1.0, v19
	v_rcp_f32_e32 v19, v19
	s_nop 0
	v_mul_f32_e32 v18, v19, v18
	v_mul_f32_e32 v12, v12, v18
	v_mul_f32_e32 v18, 0x3d372713, v16
	v_mul_f32_e32 v18, v18, v16
	v_fma_f32 v18, v18, v16, v16
	v_mul_f32_e32 v18, 0x3f4c422a, v18
	v_add_f32_e32 v18, v18, v18
	v_mul_f32_e32 v18, 0xbfb8aa3b, v18
	v_exp_f32_e32 v18, v18
	s_nop 0
	v_add_f32_e32 v18, 1.0, v18
	v_rcp_f32_e32 v18, v18
	s_nop 0
	v_mul_f32_e32 v16, v18, v16
	v_mul_f32_e32 v13, v13, v16
	v_cvt_pk_bf16_f32 v12, v12, v13
	v_lshlrev_b32_e32 v13, 16, v17
	v_mul_f32_e32 v16, 0x3d372713, v13
	v_mul_f32_e32 v16, v16, v13
	v_fma_f32 v16, v16, v13, v13
	v_mul_f32_e32 v16, 0x3f4c422a, v16
	v_add_f32_e32 v16, v16, v16
	v_mul_f32_e32 v16, 0xbfb8aa3b, v16
	v_exp_f32_e32 v16, v16
	s_nop 0
	v_add_f32_e32 v16, 1.0, v16
	v_rcp_f32_e32 v16, v16
	s_nop 0
	v_mul_f32_e32 v13, v16, v13
	v_mul_f32_e32 v13, v14, v13
	v_and_b32_e32 v14, 0xffff0000, v17
	v_mul_f32_e32 v16, 0x3d372713, v14
	v_mul_f32_e32 v16, v16, v14
	v_fma_f32 v16, v16, v14, v14
	v_mul_f32_e32 v16, 0x3f4c422a, v16
	v_add_f32_e32 v16, v16, v16
	v_mul_f32_e32 v16, 0xbfb8aa3b, v16
	v_exp_f32_e32 v16, v16
	s_nop 0
	v_add_f32_e32 v16, 1.0, v16
	v_rcp_f32_e32 v16, v16
	s_nop 0
	v_mul_f32_e32 v14, v16, v14
	v_mul_f32_e32 v14, v15, v14
	v_cvt_pk_bf16_f32 v13, v13, v14
	v_lshl_add_u64 v[14:15], v[42:43], 0, v[34:35]
	ds_bpermute_b32 v118, v109, v12
	ds_bpermute_b32 v119, v109, v13
	s_waitcnt lgkmcnt(2)
	global_store_dwordx2 v[112:113], v[116:117], off
	v_mov_b32_e32 v12, v68
	v_mov_b32_e32 v13, v69
	v_lshlrev_b32_e32 v14, 16, v12
	v_mul_f32_e32 v15, 0x3d372713, v14
	v_mul_f32_e32 v15, v15, v14
	v_fma_f32 v15, v15, v14, v14
	v_mul_f32_e32 v15, 0x3f4c422a, v15
	v_add_f32_e32 v15, v15, v15
	v_mul_f32_e32 v15, 0xbfb8aa3b, v15
	v_exp_f32_e32 v15, v15
	v_and_b32_e32 v12, 0xffff0000, v12
	v_add_f32_e32 v15, 1.0, v15
	v_rcp_f32_e32 v15, v15
	s_nop 0
	v_mul_f32_e32 v14, v15, v14
	v_mul_f32_e32 v8, v8, v14
	v_mul_f32_e32 v14, 0x3d372713, v12
	v_mul_f32_e32 v14, v14, v12
	v_fma_f32 v14, v14, v12, v12
	v_mul_f32_e32 v14, 0x3f4c422a, v14
	v_add_f32_e32 v14, v14, v14
	v_mul_f32_e32 v14, 0xbfb8aa3b, v14
	v_exp_f32_e32 v14, v14
	s_nop 0
	v_add_f32_e32 v14, 1.0, v14
	v_rcp_f32_e32 v14, v14
	s_nop 0
	v_mul_f32_e32 v12, v14, v12
	v_mul_f32_e32 v9, v9, v12
	v_cvt_pk_bf16_f32 v8, v8, v9
	v_lshlrev_b32_e32 v9, 16, v13
	v_mul_f32_e32 v12, 0x3d372713, v9
	v_mul_f32_e32 v12, v12, v9
	v_fma_f32 v12, v12, v9, v9
	v_mul_f32_e32 v12, 0x3f4c422a, v12
	v_add_f32_e32 v12, v12, v12
	v_mul_f32_e32 v12, 0xbfb8aa3b, v12
	v_exp_f32_e32 v12, v12
	s_nop 0
	v_add_f32_e32 v12, 1.0, v12
	v_rcp_f32_e32 v12, v12
	s_nop 0
	v_mul_f32_e32 v9, v12, v9
	v_mul_f32_e32 v9, v10, v9
	v_and_b32_e32 v10, 0xffff0000, v13
	v_mul_f32_e32 v12, 0x3d372713, v10
	v_mul_f32_e32 v12, v12, v10
	v_fma_f32 v12, v12, v10, v10
	v_mul_f32_e32 v12, 0x3f4c422a, v12
	v_add_f32_e32 v12, v12, v12
	v_mul_f32_e32 v12, 0xbfb8aa3b, v12
	v_exp_f32_e32 v12, v12
	s_nop 0
	v_add_f32_e32 v12, 1.0, v12
	v_rcp_f32_e32 v12, v12
	s_nop 0
	v_mul_f32_e32 v10, v12, v10
	v_mul_f32_e32 v10, v11, v10
	v_cvt_pk_bf16_f32 v9, v9, v10
	v_lshl_add_u64 v[10:11], v[42:43], 0, v[36:37]
	ds_bpermute_b32 v116, v109, v8
	ds_bpermute_b32 v117, v109, v9
	s_waitcnt lgkmcnt(2)
	global_store_dwordx2 v[112:113], v[118:119], off offset:32
	v_mov_b32_e32 v8, v70
	v_mov_b32_e32 v9, v71
	v_lshlrev_b32_e32 v10, 16, v8
	v_mul_f32_e32 v11, 0x3d372713, v10
	v_mul_f32_e32 v11, v11, v10
	v_fma_f32 v11, v11, v10, v10
	v_mul_f32_e32 v11, 0x3f4c422a, v11
	v_add_f32_e32 v11, v11, v11
	v_mul_f32_e32 v11, 0xbfb8aa3b, v11
	v_exp_f32_e32 v11, v11
	v_and_b32_e32 v8, 0xffff0000, v8
	v_add_f32_e32 v11, 1.0, v11
	v_rcp_f32_e32 v11, v11
	s_nop 0
	v_mul_f32_e32 v10, v11, v10
	v_mul_f32_e32 v4, v4, v10
	v_mul_f32_e32 v10, 0x3d372713, v8
	v_mul_f32_e32 v10, v10, v8
	v_fma_f32 v10, v10, v8, v8
	v_mul_f32_e32 v10, 0x3f4c422a, v10
	v_add_f32_e32 v10, v10, v10
	v_mul_f32_e32 v10, 0xbfb8aa3b, v10
	v_exp_f32_e32 v10, v10
	s_nop 0
	v_add_f32_e32 v10, 1.0, v10
	v_rcp_f32_e32 v10, v10
	s_nop 0
	v_mul_f32_e32 v8, v10, v8
	v_mul_f32_e32 v5, v5, v8
	v_cvt_pk_bf16_f32 v4, v4, v5
	v_lshlrev_b32_e32 v5, 16, v9
	v_mul_f32_e32 v8, 0x3d372713, v5
	v_mul_f32_e32 v8, v8, v5
	v_fma_f32 v8, v8, v5, v5
	v_mul_f32_e32 v8, 0x3f4c422a, v8
	v_add_f32_e32 v8, v8, v8
	v_mul_f32_e32 v8, 0xbfb8aa3b, v8
	v_exp_f32_e32 v8, v8
	s_nop 0
	v_add_f32_e32 v8, 1.0, v8
	v_rcp_f32_e32 v8, v8
	s_nop 0
	v_mul_f32_e32 v5, v8, v5
	v_mul_f32_e32 v5, v6, v5
	v_and_b32_e32 v6, 0xffff0000, v9
	v_mul_f32_e32 v8, 0x3d372713, v6
	v_mul_f32_e32 v8, v8, v6
	v_fma_f32 v8, v8, v6, v6
	v_mul_f32_e32 v8, 0x3f4c422a, v8
	v_add_f32_e32 v8, v8, v8
	v_mul_f32_e32 v8, 0xbfb8aa3b, v8
	v_exp_f32_e32 v8, v8
	s_nop 0
	v_add_f32_e32 v8, 1.0, v8
	v_rcp_f32_e32 v8, v8
	s_nop 0
	v_mul_f32_e32 v6, v8, v6
	v_mul_f32_e32 v2, v2, v6
	v_lshl_add_u64 v[6:7], v[42:43], 0, v[38:39]
	v_cvt_pk_bf16_f32 v5, v5, v2
	ds_bpermute_b32 v118, v109, v4
	ds_bpermute_b32 v119, v109, v5
	s_waitcnt lgkmcnt(2)
	global_store_dwordx2 v[112:113], v[116:117], off offset:64
	s_waitcnt lgkmcnt(0)
	global_store_dwordx2 v[112:113], v[118:119], off offset:96
	s_cbranch_scc0 .LBB0_1094
	s_branch .LBB0_1087
